# v30
# speedup vs baseline: 1.0064x; 1.0011x over previous
.LBB0_240:
	s_or_b64 exec, exec, s[6:7]
	s_waitcnt lgkmcnt(0)
	s_barrier
	s_waitcnt vmcnt(6)
	ds_read_b32 v0, v140
	s_mov_b64 s[6:7], -1
	s_waitcnt lgkmcnt(0)
	s_barrier
	v_cmp_lt_i32_e32 vcc, s57, v0
	v_readfirstlane_b32 s38, v0
	s_cbranch_vccnz .LBB0_235
	s_cmpk_gt_i32 s38, 0xbf
	s_cbranch_scc0 .LBB0_245
	v_mov_b32_e32 v52, v138
	s_add_i32 s7, s38, 0xffffff40
	v_mul_hi_i32 v0, v52, s63
	v_lshrrev_b32_e32 v1, 31, v0
	v_ashrrev_i32_e32 v0, 1, v0
	v_add_u32_e32 v39, v0, v1
	v_mul_lo_u32 v0, v39, 12
	v_sub_u32_e32 v40, v52, v0
	s_waitcnt vmcnt(2)
	v_add_u32_e32 v16, 0x100, v52
	s_waitcnt vmcnt(1)
	v_lshlrev_b32_e32 v20, 3, v40
	v_mul_hi_i32 v2, v16, s63
	v_ashrrev_i32_e32 v21, 31, v20
	v_lshrrev_b32_e32 v3, 31, v2
	v_ashrrev_i32_e32 v2, 1, v2
	v_lshlrev_b64 v[22:23], 1, v[20:21]
	v_add_u32_e32 v21, v2, v3
	v_mul_lo_u32 v2, v21, 12
	v_sub_u32_e32 v41, v16, v2
	v_add_u32_e32 v10, 0x200, v52
	v_lshlrev_b32_e32 v24, 3, v41
	v_mul_hi_i32 v11, v10, s63
	v_ashrrev_i32_e32 v25, 31, v24
	v_lshrrev_b32_e32 v12, 31, v11
	v_ashrrev_i32_e32 v11, 1, v11
	s_lshr_b32 s39, s7, 9
	v_lshlrev_b64 v[26:27], 1, v[24:25]
	v_add_u32_e32 v25, v11, v12
	s_lshl_b32 s40, s39, 13
	v_mul_lo_u32 v11, v25, 12
	s_bfe_u32 s6, s7, 0x30006
	v_add_u32_e32 v53, s40, v39
	v_mov_b64_e32 v[8:9], s[14:15]
	v_add_u32_e32 v54, s40, v21
	v_sub_u32_e32 v42, v10, v11
	v_add_u32_e32 v55, s40, v25
	s_lshl_b32 s7, s7, 7
	s_mul_i32 s12, s6, 0xc0
	v_mad_i64_i32 v[0:1], s[36:37], v53, s62, v[8:9]
	v_mad_i64_i32 v[2:3], s[36:37], v54, s62, v[8:9]
	v_mad_i64_i32 v[8:9], s[36:37], v55, s62, v[8:9]
	v_lshlrev_b32_e32 v28, 3, v42
	s_and_b32 s7, s7, 0x1f80
	v_lshl_add_u64 v[0:1], v[0:1], 0, s[12:13]
	v_lshl_add_u64 v[2:3], v[2:3], 0, s[12:13]
	v_ashrrev_i32_e32 v29, 31, v28
	s_lshl_b32 s36, s39, 23
	s_lshl_b32 s37, s6, 20
	s_or_b32 s7, s40, s7
	v_lshl_add_u64 v[0:1], v[0:1], 0, v[22:23]
	v_lshl_add_u64 v[4:5], v[2:3], 0, v[26:27]
	v_lshlrev_b64 v[30:31], 1, v[28:29]
	v_ashrrev_i32_e32 v34, 3, v52
	s_or_b32 s39, s37, s36
	v_ashrrev_i32_e32 v36, 3, v16
	v_and_b32_e32 v29, 31, v52
	v_ashrrev_i32_e32 v32, 1, v52
	global_load_dword v38, v113, s[26:27]
	s_nop 0
	global_load_dwordx4 v[0:3], v[0:1], off
	s_nop 0
	global_load_dwordx4 v[4:7], v[4:5], off
	v_ashrrev_i32_e32 v35, 31, v34
	s_add_u32 s36, s52, s39
	v_ashrrev_i32_e32 v37, 31, v36
	v_and_b32_e32 v32, 0xffffffe0, v32
	v_or_b32_e32 v33, s7, v29
	v_lshl_add_u64 v[8:9], v[8:9], 0, s[12:13]
	s_addc_u32 s37, s53, 0
	v_lshlrev_b64 v[48:49], 14, v[34:35]
	v_lshlrev_b32_e32 v14, 3, v52
	v_lshlrev_b64 v[50:51], 14, v[36:37]
	v_add_u32_e32 v116, v33, v32
	v_mov_b64_e32 v[32:33], s[78:79]
	v_lshl_add_u64 v[8:9], v[8:9], 0, v[30:31]
	v_lshl_add_u64 v[12:13], s[36:37], 0, v[48:49]
	v_and_b32_e32 v14, 56, v14
	v_lshl_add_u64 v[16:17], s[36:37], 0, v[50:51]
	v_bfe_u32 v35, v52, 5, 1
	v_mad_i64_i32 v[32:33], s[36:37], v116, s62, v[32:33]
	global_load_dwordx4 v[8:11], v[8:9], off
	v_lshlrev_b32_e32 v118, 1, v14
	v_mov_b32_e32 v119, v113
	v_lshl_add_u64 v[32:33], v[32:33], 0, s[12:13]
	v_lshlrev_b32_e32 v112, 4, v35
	v_lshl_add_u64 v[12:13], v[12:13], 0, v[118:119]
	v_lshl_add_u64 v[16:17], v[16:17], 0, v[118:119]
	v_lshl_add_u64 v[32:33], v[32:33], 0, v[112:113]
	global_load_dwordx4 v[12:15], v[12:13], off
	v_mul_lo_u32 v56, v39, s65
	global_load_dwordx4 v[16:19], v[16:17], off
	s_nop 0
	global_load_dwordx4 v[100:103], v[32:33], off
	global_load_dwordx4 v[96:99], v[32:33], off offset:32
	global_load_dwordx4 v[92:95], v[32:33], off offset:64
	global_load_dwordx4 v[88:91], v[32:33], off offset:96
	global_load_dwordx4 v[84:87], v[32:33], off offset:128
	global_load_dwordx4 v[80:83], v[32:33], off offset:160
	v_lshlrev_b32_e32 v33, 4, v40
	v_lshl_add_u32 v33, v56, 1, v33
	v_mul_lo_u32 v131, v34, s66
	v_mul_lo_u32 v132, v36, s66
	s_add_u32 s36, s14, s12
	s_addc_u32 s37, s15, 0
	v_lshl_add_u64 v[120:121], s[36:37], 0, v[22:23]
	v_lshl_add_u64 v[122:123], s[36:37], 0, v[26:27]
	v_lshl_add_u64 v[124:125], s[36:37], 0, v[30:31]
	s_add_u32 s36, s54, s39
	v_lshlrev_b32_e32 v114, 3, v35
	s_addc_u32 s37, s55, 0
	v_mov_b32_e32 v115, 0
	v_ashrrev_i32_e32 v117, 31, v116
	v_mul_u32_u24_e32 v133, 0xd0, v29
	s_mov_b32 s7, 0
	v_sub_u32_e32 v119, 0, v114
	v_add_u32_e32 v134, 64, v55
	v_add_u32_e32 v135, 64, v54
	v_add_u32_e32 v136, 64, v53
	v_lshlrev_b32_e32 v137, 1, v56
	v_lshlrev_b32_e32 v141, 1, v20
	v_lshlrev_b32_e32 v143, 1, v24
	v_lshlrev_b32_e32 v145, 1, v28
	s_mov_b32 s12, 0
	v_mov_b32_e32 v20, v115
	v_mov_b32_e32 v22, v115
	v_mov_b32_e32 v23, v115
	v_mov_b32_e32 v24, v115
	v_mov_b32_e32 v26, v115
	v_mov_b32_e32 v27, v115
	v_mov_b32_e32 v28, v115
	v_mov_b32_e32 v30, v115
	v_mov_b32_e32 v31, v115
	s_waitcnt vmcnt(10)
	ds_write_b128 v33, v[0:3]
	v_mul_lo_u32 v0, v21, s65
	v_lshlrev_b32_e32 v1, 4, v41
	v_lshl_add_u32 v1, v0, 1, v1
	s_waitcnt vmcnt(9)
	ds_write_b128 v1, v[4:7]
	v_mul_lo_u32 v1, v25, s65
	v_lshlrev_b32_e32 v2, 4, v42
	v_lshl_add_u32 v2, v1, 1, v2
	v_lshlrev_b32_e32 v3, 4, v52
	v_and_b32_e32 v3, 0x70, v3
	v_xor_b32_e32 v32, 0x80000000, v38
	v_or_b32_e32 v48, v48, v3
	v_or_b32_e32 v50, v50, v3
	v_mov_b32_e32 v33, v32
	v_mov_b32_e32 v34, v32
	v_mov_b32_e32 v35, v32
	v_mov_b32_e32 v36, v32
	v_mov_b32_e32 v37, v32
	v_mov_b32_e32 v38, v32
	v_mov_b32_e32 v39, v32
	v_mov_b32_e32 v40, v32
	s_waitcnt vmcnt(8)
	ds_write_b128 v2, v[8:11]
	v_lshlrev_b32_e32 v2, 1, v131
	v_add3_u32 v2, v2, v118, s67
	v_mov_b32_e32 v41, v32
	v_mov_b32_e32 v42, v32
	v_mov_b32_e32 v43, v32
	v_mov_b32_e32 v44, v32
	v_mov_b32_e32 v45, v32
	s_waitcnt vmcnt(7)
	ds_write2_b64 v2, v[12:13], v[14:15] offset1:1
	v_lshlrev_b32_e32 v2, 1, v132
	v_add3_u32 v2, v2, v118, s67
	s_waitcnt vmcnt(6)
	ds_write2_b64 v2, v[16:17], v[18:19] offset1:1
	v_mul_u32_u24_e32 v2, 0x44, v29
	v_mov_b32_e32 v46, v32
	v_mov_b32_e32 v47, v32
	v_lshl_add_u64 v[126:127], s[36:37], 0, v[48:49]
	v_lshl_add_u64 v[128:129], s[36:37], 0, v[50:51]
	v_lshlrev_b32_e32 v130, 1, v2
	v_lshlrev_b32_e32 v142, 1, v0
	v_lshlrev_b32_e32 v144, 1, v1
	v_mov_b32_e32 v0, 0
	v_mov_b32_e32 v1, v115
	v_mov_b32_e32 v2, v115
	v_mov_b32_e32 v3, v115
	v_mov_b32_e32 v4, v115
	v_mov_b32_e32 v5, v115
	v_mov_b32_e32 v6, v115
	v_mov_b32_e32 v7, v115
	v_mov_b32_e32 v8, v115
	v_mov_b32_e32 v9, v115
	v_mov_b32_e32 v10, v115
	v_mov_b32_e32 v11, v115
	v_mov_b32_e32 v12, v115
	v_mov_b32_e32 v13, v115
	v_mov_b32_e32 v14, v115
	v_mov_b32_e32 v15, v115
	v_mov_b32_e32 v16, 0
	v_mov_b32_e32 v17, v115
	v_mov_b32_e32 v18, v115
	v_mov_b32_e32 v19, v115
	v_mov_b32_e32 v21, v115
	v_mov_b32_e32 v25, v115
	v_mov_b32_e32 v29, v115
	v_mov_b32_e32 v164, v112
	v_add_u32_e32 v166, v164, v133
	v_add3_u32 v170, v164, v119, v130
	v_add_u32_e32 v186, 0x3000, v170
	v_add_u32_e32 v190, 0x4000, v170
	s_waitcnt vmcnt(0) lgkmcnt(0)
	s_barrier
.LBB0_243:
	s_and_b32 s36, s12, 1
	s_mul_i32 s37, s36, 0x5600
	ds_read_b128 v[208:211], v166
	ds_read_b128 v[212:215], v166 offset:6656
	ds_read_b128 v[216:219], v166 offset:32
	ds_read_b128 v[220:223], v166 offset:6688
	ds_read_b128 v[224:227], v166 offset:64
	ds_read_b128 v[228:231], v166 offset:6720
	ds_read_b128 v[232:235], v166 offset:96
	ds_read_b128 v[236:239], v166 offset:6752
	ds_read_b128 v[240:243], v166 offset:128
	ds_read_b128 v[244:247], v166 offset:6784
	ds_read_b128 v[248:251], v166 offset:160
	ds_read_b128 v[252:255], v166 offset:6816
	v_add_u32_e32 v150, s7, v136
	v_mad_i64_i32 v[158:159], s[40:41], v150, s62, v[120:121]
	v_add_u32_e32 v160, s7, v135
	v_add_u32_e32 v162, s7, v134
	v_mad_i64_i32 v[160:161], s[40:41], v160, s62, v[122:123]
	v_mad_i64_i32 v[162:163], s[40:41], v162, s62, v[124:125]
	global_load_dwordx4 v[104:107], v[126:127], off
	global_load_dwordx4 v[108:111], v[128:129], off
	v_lshl_add_u64 v[126:127], v[126:127], 0, s[34:35]
	v_lshl_add_u64 v[128:129], v[128:129], 0, s[34:35]
	global_load_dwordx4 v[146:149], v[158:159], off
	global_load_dwordx4 v[158:161], v[160:161], off
	global_load_dwordx4 v[150:153], v[162:163], off
	s_waitcnt lgkmcnt(11)
	v_mfma_f32_32x32x16_bf16 v[64:79], v[208:211], v[100:103], v[32:47]
	s_waitcnt lgkmcnt(10)
	v_mfma_f32_32x32x16_bf16 v[48:63], v[212:215], v[100:103], v[32:47]
	s_xor_b32 s36, s36, 1
	s_mulk_i32 s36, 0x5600
	s_add_i32 s12, s12, 1
	s_add_i32 s7, s7, 64
	s_cmpk_lg_i32 s7, 0x1fc0
	s_waitcnt lgkmcnt(9)
	v_mfma_f32_32x32x16_bf16 v[64:79], v[216:219], v[96:99], v[64:79]
	v_add3_u32 v194, s36, v137, v141
	v_add3_u32 v195, s36, v142, v143
	v_add3_u32 v196, s36, v144, v145
	s_waitcnt lgkmcnt(8)
	v_mfma_f32_32x32x16_bf16 v[48:63], v[220:223], v[96:99], v[48:63]
	s_waitcnt lgkmcnt(7)
	v_mfma_f32_32x32x16_bf16 v[64:79], v[224:227], v[92:95], v[64:79]
	s_waitcnt lgkmcnt(6)
	v_mfma_f32_32x32x16_bf16 v[48:63], v[228:231], v[92:95], v[48:63]
	s_waitcnt lgkmcnt(5)
	v_mfma_f32_32x32x16_bf16 v[64:79], v[232:235], v[88:91], v[64:79]
	s_waitcnt lgkmcnt(4)
	v_mfma_f32_32x32x16_bf16 v[48:63], v[236:239], v[88:91], v[48:63]
	s_waitcnt lgkmcnt(3)
	v_mfma_f32_32x32x16_bf16 v[64:79], v[240:243], v[84:87], v[64:79]
	s_waitcnt lgkmcnt(2)
	v_mfma_f32_32x32x16_bf16 v[48:63], v[244:247], v[84:87], v[48:63]
	v_lshl_add_u32 v154, v131, 1, s36
	v_lshl_add_u32 v155, v132, 1, s36
	v_add3_u32 v197, v154, v118, s67
	v_add3_u32 v198, v155, v118, s67
	ds_read2_b64 v[154:157], v186 offset0:128 offset1:130
	s_waitcnt lgkmcnt(2)
	v_mfma_f32_32x32x16_bf16 v[64:79], v[248:251], v[80:83], v[64:79]
	ds_read2_b64 v[162:165], v186 offset0:132 offset1:134
	ds_read2_b64 v[170:173], v190 offset0:160 offset1:162
	ds_read2_b64 v[174:177], v190 offset0:164 offset1:166
	ds_read2_b64 v[178:181], v186 offset0:136 offset1:138
	ds_read2_b64 v[182:185], v190 offset0:168 offset1:170
	ds_read2_b64 v[186:189], v186 offset0:140 offset1:142
	ds_read2_b64 v[190:193], v190 offset0:172 offset1:174
	s_nop 4
	v_exp_f32_e32 v64, v64
	s_waitcnt lgkmcnt(8)
	v_mfma_f32_32x32x16_bf16 v[48:63], v[252:255], v[80:83], v[48:63]
	v_exp_f32_e32 v65, v65
	v_exp_f32_e32 v66, v66
	v_exp_f32_e32 v67, v67
	v_exp_f32_e32 v68, v68
	v_exp_f32_e32 v69, v69
	v_exp_f32_e32 v70, v70
	v_exp_f32_e32 v71, v71
	s_nop 4
	v_exp_f32_e32 v166, v48
	v_exp_f32_e32 v167, v49
	v_exp_f32_e32 v168, v50
	v_exp_f32_e32 v169, v51
	v_cvt_pk_bf16_f32 v48, v64, v65
	v_cvt_pk_bf16_f32 v49, v66, v67
	v_cvt_pk_bf16_f32 v50, v68, v69
	v_cvt_pk_bf16_f32 v51, v70, v71
	v_exp_f32_e32 v72, v72
	v_exp_f32_e32 v73, v73
	s_waitcnt lgkmcnt(7)
	v_mfma_f32_32x32x16_bf16 v[16:31], v[154:157], v[48:51], v[16:31]
	v_exp_f32_e32 v74, v74
	v_exp_f32_e32 v75, v75
	v_exp_f32_e32 v76, v76
	v_exp_f32_e32 v77, v77
	v_exp_f32_e32 v78, v78
	v_exp_f32_e32 v79, v79
	v_add_f32_e32 v64, v115, v64
	s_waitcnt lgkmcnt(5)
	v_mfma_f32_32x32x16_bf16 v[0:15], v[170:173], v[48:51], v[0:15]
	v_add_f32_e32 v64, v65, v64
	v_add_f32_e32 v64, v66, v64
	v_add_f32_e32 v64, v67, v64
	v_exp_f32_e32 v199, v52
	v_exp_f32_e32 v200, v53
	v_exp_f32_e32 v201, v54
	v_exp_f32_e32 v202, v55
	v_cvt_pk_bf16_f32 v52, v72, v73
	v_cvt_pk_bf16_f32 v53, v74, v75
	v_cvt_pk_bf16_f32 v54, v76, v77
	v_cvt_pk_bf16_f32 v55, v78, v79
	v_add_f32_e32 v64, v68, v64
	v_cvt_pk_bf16_f32 v48, v166, v167
	v_mfma_f32_32x32x16_bf16 v[16:31], v[162:165], v[52:55], v[16:31]
	v_cvt_pk_bf16_f32 v49, v168, v169
	v_cvt_pk_bf16_f32 v50, v199, v200
	v_cvt_pk_bf16_f32 v51, v201, v202
	v_exp_f32_e32 v203, v56
	v_exp_f32_e32 v204, v57
	v_exp_f32_e32 v205, v58
	v_exp_f32_e32 v206, v59
	s_waitcnt lgkmcnt(4)
	v_mfma_f32_32x32x16_bf16 v[0:15], v[174:177], v[52:55], v[0:15]
	s_waitcnt vmcnt(2)
	ds_write_b128 v194, v[146:149]
	s_waitcnt vmcnt(1)
	ds_write_b128 v195, v[158:161]
	s_waitcnt vmcnt(0)
	ds_write_b128 v196, v[150:153]
	ds_write2_b64 v197, v[104:105], v[106:107] offset1:1
	ds_write2_b64 v198, v[108:109], v[110:111] offset1:1
	v_add_f32_e32 v52, v69, v64
	v_add_f32_e32 v52, v70, v52
	v_add_f32_e32 v52, v71, v52
	v_add_f32_e32 v52, v72, v52
	v_add_f32_e32 v52, v73, v52
	v_add_f32_e32 v52, v74, v52
	v_add_f32_e32 v52, v75, v52
	v_add_f32_e32 v52, v76, v52
	v_add_f32_e32 v52, v77, v52
	v_add_f32_e32 v52, v78, v52
	v_add_f32_e32 v52, v79, v52
	s_waitcnt lgkmcnt(8)
	v_mfma_f32_32x32x16_bf16 v[16:31], v[178:181], v[48:51], v[16:31]
	v_add_f32_e32 v52, v166, v52
	v_add_f32_e32 v52, v167, v52
	v_exp_f32_e32 v60, v60
	v_exp_f32_e32 v61, v61
	v_exp_f32_e32 v62, v62
	v_exp_f32_e32 v63, v63
	v_cvt_pk_bf16_f32 v56, v203, v204
	s_waitcnt lgkmcnt(7)
	v_mfma_f32_32x32x16_bf16 v[0:15], v[182:185], v[48:51], v[0:15]
	v_add_f32_e32 v48, v168, v52
	v_add_f32_e32 v48, v169, v48
	v_add_f32_e32 v48, v199, v48
	v_add_f32_e32 v48, v200, v48
	v_add_f32_e32 v48, v201, v48
	v_cvt_pk_bf16_f32 v57, v205, v206
	v_cvt_pk_bf16_f32 v58, v60, v61
	v_cvt_pk_bf16_f32 v59, v62, v63
	v_add_f32_e32 v48, v202, v48
	v_add_f32_e32 v48, v203, v48
	s_waitcnt lgkmcnt(6)
	v_mfma_f32_32x32x16_bf16 v[16:31], v[186:189], v[56:59], v[16:31]
	v_add_f32_e32 v48, v204, v48
	v_add_f32_e32 v48, v205, v48
	v_add_f32_e32 v48, v206, v48
	v_add_f32_e32 v48, v60, v48
	v_add_f32_e32 v48, v61, v48
	v_add_f32_e32 v48, v62, v48
	v_add_f32_e32 v115, v63, v48
	s_waitcnt lgkmcnt(5)
	v_mfma_f32_32x32x16_bf16 v[0:15], v[190:193], v[56:59], v[0:15]
	v_or_b32_e32 v164, s36, v112
	v_add_u32_e32 v166, v164, v133
	v_add3_u32 v170, v164, v119, v130
	v_add_u32_e32 v186, 0x3000, v170
	v_add_u32_e32 v190, 0x4000, v170
	s_waitcnt lgkmcnt(0)
	s_barrier
	s_cbranch_scc1 .LBB0_243
	v_add_u32_e32 v72, v112, v133
	ds_read_b128 v[64:67], v72 offset:22016
	ds_read_b128 v[68:71], v72 offset:22048
	s_lshl_b32 s12, s6, 7
	s_mov_b64 s[6:7], 0
	s_waitcnt lgkmcnt(1)
	v_mfma_f32_32x32x16_bf16 v[48:63], v[64:67], v[100:103], v[32:47]
	s_waitcnt lgkmcnt(0)
	v_mfma_f32_32x32x16_bf16 v[48:63], v[68:71], v[96:99], v[48:63]
	ds_read_b128 v[64:67], v72 offset:22080
	ds_read_b128 v[68:71], v72 offset:22112
	s_waitcnt lgkmcnt(1)
	v_mfma_f32_32x32x16_bf16 v[48:63], v[64:67], v[92:95], v[48:63]
	s_waitcnt lgkmcnt(0)
	v_mfma_f32_32x32x16_bf16 v[48:63], v[68:71], v[88:91], v[48:63]
	ds_read_b128 v[64:67], v72 offset:22144
	ds_read_b128 v[68:71], v72 offset:22176
	s_waitcnt lgkmcnt(1)
	v_mfma_f32_32x32x16_bf16 v[48:63], v[64:67], v[84:87], v[48:63]
	s_waitcnt lgkmcnt(0)
	v_mfma_f32_32x32x16_bf16 v[48:63], v[68:71], v[80:83], v[48:63]
	ds_read_b128 v[64:67], v72 offset:28672
	ds_read_b128 v[68:71], v72 offset:28704
	s_waitcnt lgkmcnt(1)
	v_mfma_f32_32x32x16_bf16 v[32:47], v[64:67], v[100:103], v[32:47]
	s_nop 7
	v_exp_f32_e32 v76, v48
	v_exp_f32_e32 v77, v49
	v_exp_f32_e32 v78, v50
	v_exp_f32_e32 v79, v51
	s_waitcnt lgkmcnt(0)
	v_mfma_f32_32x32x16_bf16 v[32:47], v[68:71], v[96:99], v[32:47]
	ds_read_b128 v[64:67], v72 offset:28736
	ds_read_b128 v[68:71], v72 offset:28768
	s_waitcnt lgkmcnt(1)
	v_mfma_f32_32x32x16_bf16 v[32:47], v[64:67], v[92:95], v[32:47]
	ds_read_b128 v[64:67], v72 offset:28800
	ds_read_b128 v[72:75], v72 offset:28832
	v_exp_f32_e32 v92, v56
	v_exp_f32_e32 v93, v61
	v_exp_f32_e32 v94, v62
	v_exp_f32_e32 v95, v63
	s_nop 0
	v_cvt_pk_bf16_f32 v51, v94, v95
	s_waitcnt lgkmcnt(2)
	v_mfma_f32_32x32x16_bf16 v[32:47], v[68:71], v[88:91], v[32:47]
	v_exp_f32_e32 v88, v52
	v_exp_f32_e32 v89, v53
	v_exp_f32_e32 v90, v54
	v_exp_f32_e32 v91, v55
	s_waitcnt lgkmcnt(1)
	v_mfma_f32_32x32x16_bf16 v[32:47], v[64:67], v[84:87], v[32:47]
	v_exp_f32_e32 v84, v57
	v_exp_f32_e32 v85, v58
	v_exp_f32_e32 v86, v59
	v_exp_f32_e32 v87, v60
	v_cvt_pk_bf16_f32 v48, v92, v84
	v_cvt_pk_bf16_f32 v49, v85, v86
	s_waitcnt lgkmcnt(0)
	v_mfma_f32_32x32x16_bf16 v[32:47], v[72:75], v[80:83], v[32:47]
	v_cvt_pk_bf16_f32 v50, v87, v93
	s_nop 10
	v_exp_f32_e32 v72, v32
	v_cvt_pk_bf16_f32 v32, v76, v77
	v_add_f32_e32 v76, v115, v76
	v_add_f32_e32 v76, v77, v76
	v_add_f32_e32 v76, v78, v76
	v_add_f32_e32 v76, v79, v76
	v_add_f32_e32 v76, v88, v76
	v_add_f32_e32 v76, v89, v76
	v_add_f32_e32 v76, v90, v76
	v_add_f32_e32 v76, v91, v76
	v_add_f32_e32 v76, v92, v76
	v_add_f32_e32 v76, v84, v76
	v_add_f32_e32 v76, v85, v76
	v_exp_f32_e32 v100, v44
	v_add3_u32 v44, v112, v119, v130
	v_add_f32_e32 v76, v86, v76
	v_exp_f32_e32 v73, v33
	v_add_u32_e32 v104, 0x8800, v44
	v_add_u32_e32 v105, 0x9800, v44
	v_add_f32_e32 v76, v87, v76
	v_exp_f32_e32 v80, v36
	v_exp_f32_e32 v81, v37
	v_exp_f32_e32 v82, v38
	v_exp_f32_e32 v83, v39
	v_exp_f32_e32 v96, v40
	v_exp_f32_e32 v97, v41
	v_exp_f32_e32 v98, v42
	v_exp_f32_e32 v99, v43
	v_exp_f32_e32 v101, v45
	v_exp_f32_e32 v102, v46
	v_exp_f32_e32 v103, v47
	ds_read2_b64 v[36:39], v104 offset0:64 offset1:66
	ds_read2_b64 v[40:43], v104 offset0:68 offset1:70
	ds_read2_b64 v[44:47], v105 offset0:96 offset1:98
	v_add_f32_e32 v76, v93, v76
	v_exp_f32_e32 v74, v34
	v_add_f32_e32 v76, v94, v76
	v_exp_f32_e32 v75, v35
	v_add_f32_e32 v76, v95, v76
	v_cvt_pk_bf16_f32 v56, v72, v73
	v_add_f32_e32 v72, v72, v76
	v_add_f32_e32 v72, v73, v72
	v_add_f32_e32 v72, v74, v72
	v_cvt_pk_bf16_f32 v33, v78, v79
	v_cvt_pk_bf16_f32 v34, v88, v89
	v_cvt_pk_bf16_f32 v35, v90, v91
	v_add_f32_e32 v72, v75, v72
	ds_read2_b64 v[52:55], v105 offset0:100 offset1:102
	s_waitcnt lgkmcnt(3)
	v_mfma_f32_32x32x16_bf16 v[16:31], v[36:39], v[32:35], v[16:31]
	v_add_f32_e32 v36, v80, v72
	v_add_f32_e32 v36, v81, v36
	v_add_f32_e32 v36, v82, v36
	v_add_f32_e32 v36, v83, v36
	v_add_f32_e32 v36, v96, v36
	v_add_f32_e32 v36, v97, v36
	v_add_f32_e32 v36, v98, v36
	s_waitcnt lgkmcnt(1)
	v_mfma_f32_32x32x16_bf16 v[0:15], v[44:47], v[32:35], v[0:15]
	v_add_f32_e32 v32, v99, v36
	v_add_f32_e32 v32, v100, v32
	v_add_f32_e32 v32, v101, v32
	v_add_f32_e32 v32, v102, v32
	v_and_b32_e32 v33, 64, v139
	v_add_f32_e32 v44, v103, v32
	v_xor_b32_e32 v32, 32, v139
	v_mfma_f32_32x32x16_bf16 v[16:31], v[40:43], v[48:51], v[16:31]
	v_add_u32_e32 v33, 64, v33
	v_cmp_lt_i32_e32 vcc, v32, v33
	ds_read2_b64 v[60:63], v104 offset0:72 offset1:74
	ds_read2_b64 v[64:67], v105 offset0:104 offset1:106
	v_cndmask_b32_e32 v32, v139, v32, vcc
	v_lshlrev_b32_e32 v32, 2, v32
	ds_bpermute_b32 v40, v32, v44
	v_cvt_pk_bf16_f32 v57, v74, v75
	s_waitcnt lgkmcnt(3)
	v_mfma_f32_32x32x16_bf16 v[0:15], v[52:55], v[48:51], v[0:15]
	v_cvt_pk_bf16_f32 v58, v80, v81
	v_cvt_pk_bf16_f32 v59, v82, v83
	s_waitcnt lgkmcnt(0)
	v_add_f32_e32 v40, v44, v40
	ds_read2_b64 v[32:35], v104 offset0:76 offset1:78
	ds_read2_b64 v[36:39], v105 offset0:108 offset1:110
	v_div_scale_f32 v41, s[36:37], v40, v40, 1.0
	v_rcp_f32_e32 v42, v41
	v_mfma_f32_32x32x16_bf16 v[16:31], v[60:63], v[56:59], v[16:31]
	v_cvt_pk_bf16_f32 v68, v96, v97
	v_cvt_pk_bf16_f32 v69, v98, v99
	v_cvt_pk_bf16_f32 v70, v100, v101
	v_cvt_pk_bf16_f32 v71, v102, v103
	v_fma_f32 v43, -v41, v42, 1.0
	v_fmac_f32_e32 v42, v43, v42
	v_div_scale_f32 v43, vcc, 1.0, v40, 1.0
	v_mfma_f32_32x32x16_bf16 v[0:15], v[64:67], v[56:59], v[0:15]
	v_mul_f32_e32 v44, v43, v42
	v_fma_f32 v45, -v41, v44, v43
	v_fmac_f32_e32 v44, v45, v42
	v_fma_f32 v41, -v41, v44, v43
	v_div_fmas_f32 v41, v41, v42, v44
	v_lshlrev_b64 v[42:43], 10, v[116:117]
	v_div_fixup_f32 v40, v41, v40, 1.0
	s_waitcnt lgkmcnt(1)
	v_mfma_f32_32x32x16_bf16 v[16:31], v[32:35], v[68:71], v[16:31]
	v_lshl_add_u64 v[42:43], s[8:9], 0, v[42:43]
	v_lshl_add_u64 v[32:33], v[42:43], 0, s[12:13]
	v_mov_b32_e32 v115, v113
	v_lshl_add_u64 v[32:33], v[32:33], 0, v[114:115]
	s_waitcnt lgkmcnt(0)
	s_barrier
	v_mfma_f32_32x32x16_bf16 v[0:15], v[36:39], v[68:71], v[0:15]
	s_nop 4
	v_mul_f32_e64 v16, v16, v40
	v_mul_f32_e64 v17, v17, v40
	v_mul_f32_e64 v18, v18, v40
	v_mul_f32_e64 v19, v19, v40
	v_cvt_pk_bf16_f32 v16, v16, v17
	v_cvt_pk_bf16_f32 v17, v18, v19
	global_store_dwordx2 v[32:33], v[16:17], off
	v_pk_mul_f32 v[16:17], v[20:21], v[40:41] op_sel_hi:[1,0]
	v_pk_mul_f32 v[18:19], v[22:23], v[40:41] op_sel_hi:[1,0]
	v_pk_mul_f32 v[0:1], v[0:1], v[40:41] op_sel_hi:[1,0]
	v_pk_mul_f32 v[2:3], v[2:3], v[40:41] op_sel_hi:[1,0]
	v_cvt_pk_bf16_f32 v0, v0, v1
	v_cvt_pk_bf16_f32 v1, v2, v3
	global_store_dwordx2 v[32:33], v[0:1], off offset:64
	v_pk_mul_f32 v[0:1], v[4:5], v[40:41] op_sel_hi:[1,0]
	v_pk_mul_f32 v[2:3], v[6:7], v[40:41] op_sel_hi:[1,0]
	v_cvt_pk_bf16_f32 v16, v16, v17
	v_cvt_pk_bf16_f32 v17, v18, v19
	v_cvt_pk_bf16_f32 v0, v0, v1
	v_cvt_pk_bf16_f32 v1, v2, v3
	global_store_dwordx2 v[32:33], v[16:17], off offset:16
	v_pk_mul_f32 v[16:17], v[24:25], v[40:41] op_sel_hi:[1,0]
	v_pk_mul_f32 v[18:19], v[26:27], v[40:41] op_sel_hi:[1,0]
	global_store_dwordx2 v[32:33], v[0:1], off offset:80
	v_pk_mul_f32 v[0:1], v[8:9], v[40:41] op_sel_hi:[1,0]
	v_pk_mul_f32 v[2:3], v[10:11], v[40:41] op_sel_hi:[1,0]
	v_cvt_pk_bf16_f32 v16, v16, v17
	v_cvt_pk_bf16_f32 v17, v18, v19
	v_cvt_pk_bf16_f32 v0, v0, v1
	v_cvt_pk_bf16_f32 v1, v2, v3
	global_store_dwordx2 v[32:33], v[16:17], off offset:32
	v_pk_mul_f32 v[16:17], v[28:29], v[40:41] op_sel_hi:[1,0]
	v_pk_mul_f32 v[18:19], v[30:31], v[40:41] op_sel_hi:[1,0]
	global_store_dwordx2 v[32:33], v[0:1], off offset:96
	v_pk_mul_f32 v[0:1], v[12:13], v[40:41] op_sel_hi:[1,0]
	v_pk_mul_f32 v[2:3], v[14:15], v[40:41] op_sel_hi:[1,0]
	v_cvt_pk_bf16_f32 v16, v16, v17
	v_cvt_pk_bf16_f32 v17, v18, v19
	v_cvt_pk_bf16_f32 v0, v0, v1
	v_cvt_pk_bf16_f32 v1, v2, v3
	global_store_dwordx2 v[32:33], v[16:17], off offset:48
	global_store_dwordx2 v[32:33], v[0:1], off offset:112
